# pooled_phase rewritten: LDS-DMA staging of 32-token blocks (+15 halo rows) then per-wave (group, token pair) window sums from LDS, same summation order; on top of v51 (dma+cvt2+sc1 P1)
# speedup vs baseline: 1.0193x; 1.0193x over previous
.LBB0_189:
	v_readlane_b32 s0, v254, 24
	v_readlane_b32 s4, v255, 22
	v_readlane_b32 s1, v254, 25
	v_readlane_b32 s5, v255, 23
	s_and_b64 s[0:1], s[4:5], s[0:1]
	s_andn2_b64 vcc, exec, s[0:1]
	s_mov_b64 s[0:1], -1
	s_waitcnt lgkmcnt(0)
	s_barrier
	s_cbranch_vccz .LBB0_257
	v_readlane_b32 s0, v254, 22
	v_readlane_b32 s4, v255, 22
	v_readlane_b32 s1, v254, 23
	v_readlane_b32 s5, v255, 23
	s_and_b64 s[0:1], s[0:1], s[4:5]
	s_and_b64 s[0:1], s[0:1], exec
	s_cselect_b32 s4, 64, 0
	s_mov_b64 s[6:7], exec
	s_mov_b64 exec, -1
	s_sub_i32 s5, s2, s4
	s_sub_i32 s16, s80, s4
	s_mov_b64 s[0:1], s[88:89]
	s_load_dwordx2 s[8:9], s[0:1], 0x98
	v_mbcnt_lo_u32_b32 v0, -1, 0
	v_mbcnt_hi_u32_b32 v0, -1, v0
	v_lshlrev_b32_e32 v2, 4, v0
	v_and_b32_e32 v3, 31, v0
	v_lshlrev_b32_e32 v3, 4, v3
	v_lshrrev_b32_e32 v5, 5, v0
	v_lshl_add_u32 v4, v5, 9, v3
	v_lshl_add_u32 v3, v5, 11, v3
	s_waitcnt lgkmcnt(0)
	s_add_u32 s10, s8, 0x3ac00000
	s_addc_u32 s11, s9, 0
	s_add_u32 s8, s8, 0x12802800
	s_addc_u32 s9, s9, 0
	s_cmp_lt_i32 s5, 0
	s_cbranch_scc1 .Lpool_end
.Lpool_blk:
	s_cmp_ge_i32 s5, 512
	s_cbranch_scc1 .Lpool_end
	s_lshl_b32 s12, s5, 5
	s_and_b32 s13, s12, 0xfff
	s_lshr_b32 s14, s83, 6
.Lpool_stage:
	s_lshr_b32 s15, s14, 1
	s_lshl_b32 s17, s14, 10
	s_cmp_lg_u32 s13, 0
	s_cbranch_scc1 .Lpool_ld
	s_cmp_ge_u32 s15, 15
	s_cbranch_scc1 .Lpool_ld
	v_mov_b32_e32 v8, 0
	v_mov_b32_e32 v9, 0
	v_mov_b32_e32 v10, 0
	v_mov_b32_e32 v11, 0
	v_add_u32_e32 v13, s17, v2
	ds_write_b128 v13, v[8:11]
	s_branch .Lpool_nx
.Lpool_ld:
	s_add_i32 s18, s12, s15
	s_add_i32 s18, s18, -15
	s_mul_i32 s18, s18, s87
	s_and_b32 s19, s14, 1
	s_lshl_b32 s19, s19, 10
	s_add_i32 s0, s18, s19
	s_add_u32 s18, s8, s0
	s_addc_u32 s19, s9, 0
	s_mov_b32 m0, s17
	s_nop 0
	global_load_lds_dwordx4 v2, s[18:19]
.Lpool_nx:
	s_add_i32 s14, s14, 8
	s_cmp_lt_u32 s14, 94
	s_cbranch_scc1 .Lpool_stage
	s_waitcnt vmcnt(0) lgkmcnt(0)
	s_barrier
	s_lshr_b32 s20, s83, 5
	s_mov_b32 s14, 0
.Lpool_tp:
	s_lshl_b32 s21, s20, 1
	s_add_i32 s21, s21, s12
	v_add_u32_e32 v6, s21, v5
	v_and_b32_e32 v6, 0xfff, v6
	v_add_u32_e32 v6, 1, v6
	s_lshl_b32 s17, s20, 12
	v_add_u32_e32 v7, s17, v3
	s_lshl_b32 s17, s21, 9
	v_add_u32_e32 v0, s17, v4
	ds_read_b128 v[16:19], v7 offset:30720
	ds_read_b128 v[20:23], v7 offset:28672
	v_min_u32_e32 v97, 2, v6
	v_cvt_f32_u32_e32 v97, v97
	v_div_scale_f32 v98, s[0:1], v97, v97, 1.0
	v_rcp_f32_e32 v99, v98
	v_div_scale_f32 v8, vcc, 1.0, v97, 1.0
	v_fma_f32 v9, -v98, v99, 1.0
	v_fmac_f32_e32 v99, v9, v99
	v_mul_f32_e32 v10, v8, v99
	v_fma_f32 v11, -v98, v10, v8
	v_fmac_f32_e32 v10, v11, v99
	v_fma_f32 v8, -v98, v10, v8
	v_div_fmas_f32 v8, v8, v99, v10
	v_div_fixup_f32 v96, v8, v97, 1.0
	s_waitcnt lgkmcnt(1)
	v_lshlrev_b32_e32 v88, 16, v16
	v_and_b32_e32 v89, 0xffff0000, v16
	v_lshlrev_b32_e32 v90, 16, v17
	v_and_b32_e32 v91, 0xffff0000, v17
	v_lshlrev_b32_e32 v92, 16, v18
	v_and_b32_e32 v93, 0xffff0000, v18
	v_lshlrev_b32_e32 v94, 16, v19
	v_and_b32_e32 v95, 0xffff0000, v19
	s_waitcnt lgkmcnt(0)
	v_lshlrev_b32_e32 v8, 16, v20
	v_and_b32_e32 v9, 0xffff0000, v20
	v_lshlrev_b32_e32 v10, 16, v21
	v_and_b32_e32 v11, 0xffff0000, v21
	v_lshlrev_b32_e32 v12, 16, v22
	v_and_b32_e32 v13, 0xffff0000, v22
	v_lshlrev_b32_e32 v14, 16, v23
	v_and_b32_e32 v15, 0xffff0000, v23
	v_pk_add_f32 v[80:81], v[88:89], v[8:9]
	v_pk_add_f32 v[82:83], v[90:91], v[10:11]
	v_pk_add_f32 v[84:85], v[92:93], v[12:13]
	v_pk_add_f32 v[86:87], v[94:95], v[14:15]
	v_pk_fma_f32 v[80:81], v[96:97], v[80:81], v[88:89] op_sel_hi:[0,1,1] neg_lo:[0,0,1] neg_hi:[0,0,1]
	v_pk_fma_f32 v[82:83], v[96:97], v[82:83], v[90:91] op_sel_hi:[0,1,1] neg_lo:[0,0,1] neg_hi:[0,0,1]
	v_pk_fma_f32 v[84:85], v[96:97], v[84:85], v[92:93] op_sel_hi:[0,1,1] neg_lo:[0,0,1] neg_hi:[0,0,1]
	v_pk_fma_f32 v[86:87], v[96:97], v[86:87], v[94:95] op_sel_hi:[0,1,1] neg_lo:[0,0,1] neg_hi:[0,0,1]
	v_cvt_pk_bf16_f32 v8, v80, v81
	v_cvt_pk_bf16_f32 v9, v82, v83
	v_cvt_pk_bf16_f32 v10, v84, v85
	v_cvt_pk_bf16_f32 v11, v86, v87
	global_store_dwordx4 v0, v[8:11], s[10:11]
	ds_read_b128 v[16:19], v7 offset:31232
	ds_read_b128 v[20:23], v7 offset:29184
	ds_read_b128 v[24:27], v7 offset:27136
	ds_read_b128 v[28:31], v7 offset:25088
	v_min_u32_e32 v97, 4, v6
	v_cvt_f32_u32_e32 v97, v97
	v_div_scale_f32 v98, s[0:1], v97, v97, 1.0
	v_rcp_f32_e32 v99, v98
	v_div_scale_f32 v8, vcc, 1.0, v97, 1.0
	v_fma_f32 v9, -v98, v99, 1.0
	v_fmac_f32_e32 v99, v9, v99
	v_mul_f32_e32 v10, v8, v99
	v_fma_f32 v11, -v98, v10, v8
	v_fmac_f32_e32 v10, v11, v99
	v_fma_f32 v8, -v98, v10, v8
	v_div_fmas_f32 v8, v8, v99, v10
	v_div_fixup_f32 v96, v8, v97, 1.0
	s_waitcnt lgkmcnt(3)
	v_lshlrev_b32_e32 v88, 16, v16
	v_and_b32_e32 v89, 0xffff0000, v16
	v_lshlrev_b32_e32 v90, 16, v17
	v_and_b32_e32 v91, 0xffff0000, v17
	v_lshlrev_b32_e32 v92, 16, v18
	v_and_b32_e32 v93, 0xffff0000, v18
	v_lshlrev_b32_e32 v94, 16, v19
	v_and_b32_e32 v95, 0xffff0000, v19
	s_waitcnt lgkmcnt(2)
	v_lshlrev_b32_e32 v8, 16, v20
	v_and_b32_e32 v9, 0xffff0000, v20
	v_lshlrev_b32_e32 v10, 16, v21
	v_and_b32_e32 v11, 0xffff0000, v21
	v_lshlrev_b32_e32 v12, 16, v22
	v_and_b32_e32 v13, 0xffff0000, v22
	v_lshlrev_b32_e32 v14, 16, v23
	v_and_b32_e32 v15, 0xffff0000, v23
	v_pk_add_f32 v[80:81], v[88:89], v[8:9]
	v_pk_add_f32 v[82:83], v[90:91], v[10:11]
	v_pk_add_f32 v[84:85], v[92:93], v[12:13]
	v_pk_add_f32 v[86:87], v[94:95], v[14:15]
	s_waitcnt lgkmcnt(1)
	v_lshlrev_b32_e32 v8, 16, v24
	v_and_b32_e32 v9, 0xffff0000, v24
	v_lshlrev_b32_e32 v10, 16, v25
	v_and_b32_e32 v11, 0xffff0000, v25
	v_lshlrev_b32_e32 v12, 16, v26
	v_and_b32_e32 v13, 0xffff0000, v26
	v_lshlrev_b32_e32 v14, 16, v27
	v_and_b32_e32 v15, 0xffff0000, v27
	v_pk_add_f32 v[80:81], v[80:81], v[8:9]
	v_pk_add_f32 v[82:83], v[82:83], v[10:11]
	v_pk_add_f32 v[84:85], v[84:85], v[12:13]
	v_pk_add_f32 v[86:87], v[86:87], v[14:15]
	s_waitcnt lgkmcnt(0)
	v_lshlrev_b32_e32 v8, 16, v28
	v_and_b32_e32 v9, 0xffff0000, v28
	v_lshlrev_b32_e32 v10, 16, v29
	v_and_b32_e32 v11, 0xffff0000, v29
	v_lshlrev_b32_e32 v12, 16, v30
	v_and_b32_e32 v13, 0xffff0000, v30
	v_lshlrev_b32_e32 v14, 16, v31
	v_and_b32_e32 v15, 0xffff0000, v31
	v_pk_add_f32 v[80:81], v[80:81], v[8:9]
	v_pk_add_f32 v[82:83], v[82:83], v[10:11]
	v_pk_add_f32 v[84:85], v[84:85], v[12:13]
	v_pk_add_f32 v[86:87], v[86:87], v[14:15]
	v_pk_fma_f32 v[80:81], v[96:97], v[80:81], v[88:89] op_sel_hi:[0,1,1] neg_lo:[0,0,1] neg_hi:[0,0,1]
	v_pk_fma_f32 v[82:83], v[96:97], v[82:83], v[90:91] op_sel_hi:[0,1,1] neg_lo:[0,0,1] neg_hi:[0,0,1]
	v_pk_fma_f32 v[84:85], v[96:97], v[84:85], v[92:93] op_sel_hi:[0,1,1] neg_lo:[0,0,1] neg_hi:[0,0,1]
	v_pk_fma_f32 v[86:87], v[96:97], v[86:87], v[94:95] op_sel_hi:[0,1,1] neg_lo:[0,0,1] neg_hi:[0,0,1]
	v_cvt_pk_bf16_f32 v8, v80, v81
	v_cvt_pk_bf16_f32 v9, v82, v83
	v_cvt_pk_bf16_f32 v10, v84, v85
	v_cvt_pk_bf16_f32 v11, v86, v87
	v_add_u32_e32 v98, 0x800000, v0
	global_store_dwordx4 v98, v[8:11], s[10:11]
	ds_read_b128 v[16:19], v7 offset:31744
	ds_read_b128 v[20:23], v7 offset:29696
	ds_read_b128 v[24:27], v7 offset:27648
	ds_read_b128 v[28:31], v7 offset:25600
	ds_read_b128 v[32:35], v7 offset:23552
	ds_read_b128 v[36:39], v7 offset:21504
	ds_read_b128 v[40:43], v7 offset:19456
	ds_read_b128 v[44:47], v7 offset:17408
	v_min_u32_e32 v97, 8, v6
	v_cvt_f32_u32_e32 v97, v97
	v_div_scale_f32 v98, s[0:1], v97, v97, 1.0
	v_rcp_f32_e32 v99, v98
	v_div_scale_f32 v8, vcc, 1.0, v97, 1.0
	v_fma_f32 v9, -v98, v99, 1.0
	v_fmac_f32_e32 v99, v9, v99
	v_mul_f32_e32 v10, v8, v99
	v_fma_f32 v11, -v98, v10, v8
	v_fmac_f32_e32 v10, v11, v99
	v_fma_f32 v8, -v98, v10, v8
	v_div_fmas_f32 v8, v8, v99, v10
	v_div_fixup_f32 v96, v8, v97, 1.0
	s_waitcnt lgkmcnt(7)
	v_lshlrev_b32_e32 v88, 16, v16
	v_and_b32_e32 v89, 0xffff0000, v16
	v_lshlrev_b32_e32 v90, 16, v17
	v_and_b32_e32 v91, 0xffff0000, v17
	v_lshlrev_b32_e32 v92, 16, v18
	v_and_b32_e32 v93, 0xffff0000, v18
	v_lshlrev_b32_e32 v94, 16, v19
	v_and_b32_e32 v95, 0xffff0000, v19
	s_waitcnt lgkmcnt(6)
	v_lshlrev_b32_e32 v8, 16, v20
	v_and_b32_e32 v9, 0xffff0000, v20
	v_lshlrev_b32_e32 v10, 16, v21
	v_and_b32_e32 v11, 0xffff0000, v21
	v_lshlrev_b32_e32 v12, 16, v22
	v_and_b32_e32 v13, 0xffff0000, v22
	v_lshlrev_b32_e32 v14, 16, v23
	v_and_b32_e32 v15, 0xffff0000, v23
	v_pk_add_f32 v[80:81], v[88:89], v[8:9]
	v_pk_add_f32 v[82:83], v[90:91], v[10:11]
	v_pk_add_f32 v[84:85], v[92:93], v[12:13]
	v_pk_add_f32 v[86:87], v[94:95], v[14:15]
	s_waitcnt lgkmcnt(5)
	v_lshlrev_b32_e32 v8, 16, v24
	v_and_b32_e32 v9, 0xffff0000, v24
	v_lshlrev_b32_e32 v10, 16, v25
	v_and_b32_e32 v11, 0xffff0000, v25
	v_lshlrev_b32_e32 v12, 16, v26
	v_and_b32_e32 v13, 0xffff0000, v26
	v_lshlrev_b32_e32 v14, 16, v27
	v_and_b32_e32 v15, 0xffff0000, v27
	v_pk_add_f32 v[80:81], v[80:81], v[8:9]
	v_pk_add_f32 v[82:83], v[82:83], v[10:11]
	v_pk_add_f32 v[84:85], v[84:85], v[12:13]
	v_pk_add_f32 v[86:87], v[86:87], v[14:15]
	s_waitcnt lgkmcnt(4)
	v_lshlrev_b32_e32 v8, 16, v28
	v_and_b32_e32 v9, 0xffff0000, v28
	v_lshlrev_b32_e32 v10, 16, v29
	v_and_b32_e32 v11, 0xffff0000, v29
	v_lshlrev_b32_e32 v12, 16, v30
	v_and_b32_e32 v13, 0xffff0000, v30
	v_lshlrev_b32_e32 v14, 16, v31
	v_and_b32_e32 v15, 0xffff0000, v31
	v_pk_add_f32 v[80:81], v[80:81], v[8:9]
	v_pk_add_f32 v[82:83], v[82:83], v[10:11]
	v_pk_add_f32 v[84:85], v[84:85], v[12:13]
	v_pk_add_f32 v[86:87], v[86:87], v[14:15]
	s_waitcnt lgkmcnt(3)
	v_lshlrev_b32_e32 v8, 16, v32
	v_and_b32_e32 v9, 0xffff0000, v32
	v_lshlrev_b32_e32 v10, 16, v33
	v_and_b32_e32 v11, 0xffff0000, v33
	v_lshlrev_b32_e32 v12, 16, v34
	v_and_b32_e32 v13, 0xffff0000, v34
	v_lshlrev_b32_e32 v14, 16, v35
	v_and_b32_e32 v15, 0xffff0000, v35
	v_pk_add_f32 v[80:81], v[80:81], v[8:9]
	v_pk_add_f32 v[82:83], v[82:83], v[10:11]
	v_pk_add_f32 v[84:85], v[84:85], v[12:13]
	v_pk_add_f32 v[86:87], v[86:87], v[14:15]
	s_waitcnt lgkmcnt(2)
	v_lshlrev_b32_e32 v8, 16, v36
	v_and_b32_e32 v9, 0xffff0000, v36
	v_lshlrev_b32_e32 v10, 16, v37
	v_and_b32_e32 v11, 0xffff0000, v37
	v_lshlrev_b32_e32 v12, 16, v38
	v_and_b32_e32 v13, 0xffff0000, v38
	v_lshlrev_b32_e32 v14, 16, v39
	v_and_b32_e32 v15, 0xffff0000, v39
	v_pk_add_f32 v[80:81], v[80:81], v[8:9]
	v_pk_add_f32 v[82:83], v[82:83], v[10:11]
	v_pk_add_f32 v[84:85], v[84:85], v[12:13]
	v_pk_add_f32 v[86:87], v[86:87], v[14:15]
	s_waitcnt lgkmcnt(1)
	v_lshlrev_b32_e32 v8, 16, v40
	v_and_b32_e32 v9, 0xffff0000, v40
	v_lshlrev_b32_e32 v10, 16, v41
	v_and_b32_e32 v11, 0xffff0000, v41
	v_lshlrev_b32_e32 v12, 16, v42
	v_and_b32_e32 v13, 0xffff0000, v42
	v_lshlrev_b32_e32 v14, 16, v43
	v_and_b32_e32 v15, 0xffff0000, v43
	v_pk_add_f32 v[80:81], v[80:81], v[8:9]
	v_pk_add_f32 v[82:83], v[82:83], v[10:11]
	v_pk_add_f32 v[84:85], v[84:85], v[12:13]
	v_pk_add_f32 v[86:87], v[86:87], v[14:15]
	s_waitcnt lgkmcnt(0)
	v_lshlrev_b32_e32 v8, 16, v44
	v_and_b32_e32 v9, 0xffff0000, v44
	v_lshlrev_b32_e32 v10, 16, v45
	v_and_b32_e32 v11, 0xffff0000, v45
	v_lshlrev_b32_e32 v12, 16, v46
	v_and_b32_e32 v13, 0xffff0000, v46
	v_lshlrev_b32_e32 v14, 16, v47
	v_and_b32_e32 v15, 0xffff0000, v47
	v_pk_add_f32 v[80:81], v[80:81], v[8:9]
	v_pk_add_f32 v[82:83], v[82:83], v[10:11]
	v_pk_add_f32 v[84:85], v[84:85], v[12:13]
	v_pk_add_f32 v[86:87], v[86:87], v[14:15]
	v_pk_fma_f32 v[80:81], v[96:97], v[80:81], v[88:89] op_sel_hi:[0,1,1] neg_lo:[0,0,1] neg_hi:[0,0,1]
	v_pk_fma_f32 v[82:83], v[96:97], v[82:83], v[90:91] op_sel_hi:[0,1,1] neg_lo:[0,0,1] neg_hi:[0,0,1]
	v_pk_fma_f32 v[84:85], v[96:97], v[84:85], v[92:93] op_sel_hi:[0,1,1] neg_lo:[0,0,1] neg_hi:[0,0,1]
	v_pk_fma_f32 v[86:87], v[96:97], v[86:87], v[94:95] op_sel_hi:[0,1,1] neg_lo:[0,0,1] neg_hi:[0,0,1]
	v_cvt_pk_bf16_f32 v8, v80, v81
	v_cvt_pk_bf16_f32 v9, v82, v83
	v_cvt_pk_bf16_f32 v10, v84, v85
	v_cvt_pk_bf16_f32 v11, v86, v87
	v_add_u32_e32 v98, 0x1000000, v0
	global_store_dwordx4 v98, v[8:11], s[10:11]
	ds_read_b128 v[16:19], v7 offset:32256
	ds_read_b128 v[20:23], v7 offset:30208
	ds_read_b128 v[24:27], v7 offset:28160
	ds_read_b128 v[28:31], v7 offset:26112
	ds_read_b128 v[32:35], v7 offset:24064
	ds_read_b128 v[36:39], v7 offset:22016
	ds_read_b128 v[40:43], v7 offset:19968
	ds_read_b128 v[44:47], v7 offset:17920
	v_min_u32_e32 v97, 16, v6
	v_cvt_f32_u32_e32 v97, v97
	v_div_scale_f32 v98, s[0:1], v97, v97, 1.0
	v_rcp_f32_e32 v99, v98
	v_div_scale_f32 v8, vcc, 1.0, v97, 1.0
	v_fma_f32 v9, -v98, v99, 1.0
	v_fmac_f32_e32 v99, v9, v99
	v_mul_f32_e32 v10, v8, v99
	v_fma_f32 v11, -v98, v10, v8
	v_fmac_f32_e32 v10, v11, v99
	v_fma_f32 v8, -v98, v10, v8
	v_div_fmas_f32 v8, v8, v99, v10
	v_div_fixup_f32 v96, v8, v97, 1.0
	s_waitcnt lgkmcnt(7)
	v_lshlrev_b32_e32 v88, 16, v16
	v_and_b32_e32 v89, 0xffff0000, v16
	v_lshlrev_b32_e32 v90, 16, v17
	v_and_b32_e32 v91, 0xffff0000, v17
	v_lshlrev_b32_e32 v92, 16, v18
	v_and_b32_e32 v93, 0xffff0000, v18
	v_lshlrev_b32_e32 v94, 16, v19
	v_and_b32_e32 v95, 0xffff0000, v19
	ds_read_b128 v[48:51], v7 offset:15872
	s_waitcnt lgkmcnt(7)
	v_lshlrev_b32_e32 v8, 16, v20
	v_and_b32_e32 v9, 0xffff0000, v20
	v_lshlrev_b32_e32 v10, 16, v21
	v_and_b32_e32 v11, 0xffff0000, v21
	v_lshlrev_b32_e32 v12, 16, v22
	v_and_b32_e32 v13, 0xffff0000, v22
	v_lshlrev_b32_e32 v14, 16, v23
	v_and_b32_e32 v15, 0xffff0000, v23
	v_pk_add_f32 v[80:81], v[88:89], v[8:9]
	v_pk_add_f32 v[82:83], v[90:91], v[10:11]
	v_pk_add_f32 v[84:85], v[92:93], v[12:13]
	v_pk_add_f32 v[86:87], v[94:95], v[14:15]
	ds_read_b128 v[52:55], v7 offset:13824
	s_waitcnt lgkmcnt(7)
	v_lshlrev_b32_e32 v8, 16, v24
	v_and_b32_e32 v9, 0xffff0000, v24
	v_lshlrev_b32_e32 v10, 16, v25
	v_and_b32_e32 v11, 0xffff0000, v25
	v_lshlrev_b32_e32 v12, 16, v26
	v_and_b32_e32 v13, 0xffff0000, v26
	v_lshlrev_b32_e32 v14, 16, v27
	v_and_b32_e32 v15, 0xffff0000, v27
	v_pk_add_f32 v[80:81], v[80:81], v[8:9]
	v_pk_add_f32 v[82:83], v[82:83], v[10:11]
	v_pk_add_f32 v[84:85], v[84:85], v[12:13]
	v_pk_add_f32 v[86:87], v[86:87], v[14:15]
	ds_read_b128 v[56:59], v7 offset:11776
	s_waitcnt lgkmcnt(7)
	v_lshlrev_b32_e32 v8, 16, v28
	v_and_b32_e32 v9, 0xffff0000, v28
	v_lshlrev_b32_e32 v10, 16, v29
	v_and_b32_e32 v11, 0xffff0000, v29
	v_lshlrev_b32_e32 v12, 16, v30
	v_and_b32_e32 v13, 0xffff0000, v30
	v_lshlrev_b32_e32 v14, 16, v31
	v_and_b32_e32 v15, 0xffff0000, v31
	v_pk_add_f32 v[80:81], v[80:81], v[8:9]
	v_pk_add_f32 v[82:83], v[82:83], v[10:11]
	v_pk_add_f32 v[84:85], v[84:85], v[12:13]
	v_pk_add_f32 v[86:87], v[86:87], v[14:15]
	ds_read_b128 v[60:63], v7 offset:9728
	s_waitcnt lgkmcnt(7)
	v_lshlrev_b32_e32 v8, 16, v32
	v_and_b32_e32 v9, 0xffff0000, v32
	v_lshlrev_b32_e32 v10, 16, v33
	v_and_b32_e32 v11, 0xffff0000, v33
	v_lshlrev_b32_e32 v12, 16, v34
	v_and_b32_e32 v13, 0xffff0000, v34
	v_lshlrev_b32_e32 v14, 16, v35
	v_and_b32_e32 v15, 0xffff0000, v35
	v_pk_add_f32 v[80:81], v[80:81], v[8:9]
	v_pk_add_f32 v[82:83], v[82:83], v[10:11]
	v_pk_add_f32 v[84:85], v[84:85], v[12:13]
	v_pk_add_f32 v[86:87], v[86:87], v[14:15]
	ds_read_b128 v[64:67], v7 offset:7680
	s_waitcnt lgkmcnt(7)
	v_lshlrev_b32_e32 v8, 16, v36
	v_and_b32_e32 v9, 0xffff0000, v36
	v_lshlrev_b32_e32 v10, 16, v37
	v_and_b32_e32 v11, 0xffff0000, v37
	v_lshlrev_b32_e32 v12, 16, v38
	v_and_b32_e32 v13, 0xffff0000, v38
	v_lshlrev_b32_e32 v14, 16, v39
	v_and_b32_e32 v15, 0xffff0000, v39
	v_pk_add_f32 v[80:81], v[80:81], v[8:9]
	v_pk_add_f32 v[82:83], v[82:83], v[10:11]
	v_pk_add_f32 v[84:85], v[84:85], v[12:13]
	v_pk_add_f32 v[86:87], v[86:87], v[14:15]
	ds_read_b128 v[68:71], v7 offset:5632
	s_waitcnt lgkmcnt(7)
	v_lshlrev_b32_e32 v8, 16, v40
	v_and_b32_e32 v9, 0xffff0000, v40
	v_lshlrev_b32_e32 v10, 16, v41
	v_and_b32_e32 v11, 0xffff0000, v41
	v_lshlrev_b32_e32 v12, 16, v42
	v_and_b32_e32 v13, 0xffff0000, v42
	v_lshlrev_b32_e32 v14, 16, v43
	v_and_b32_e32 v15, 0xffff0000, v43
	v_pk_add_f32 v[80:81], v[80:81], v[8:9]
	v_pk_add_f32 v[82:83], v[82:83], v[10:11]
	v_pk_add_f32 v[84:85], v[84:85], v[12:13]
	v_pk_add_f32 v[86:87], v[86:87], v[14:15]
	ds_read_b128 v[72:75], v7 offset:3584
	s_waitcnt lgkmcnt(7)
	v_lshlrev_b32_e32 v8, 16, v44
	v_and_b32_e32 v9, 0xffff0000, v44
	v_lshlrev_b32_e32 v10, 16, v45
	v_and_b32_e32 v11, 0xffff0000, v45
	v_lshlrev_b32_e32 v12, 16, v46
	v_and_b32_e32 v13, 0xffff0000, v46
	v_lshlrev_b32_e32 v14, 16, v47
	v_and_b32_e32 v15, 0xffff0000, v47
	v_pk_add_f32 v[80:81], v[80:81], v[8:9]
	v_pk_add_f32 v[82:83], v[82:83], v[10:11]
	v_pk_add_f32 v[84:85], v[84:85], v[12:13]
	v_pk_add_f32 v[86:87], v[86:87], v[14:15]
	ds_read_b128 v[76:79], v7 offset:1536
	s_waitcnt lgkmcnt(7)
	v_lshlrev_b32_e32 v8, 16, v48
	v_and_b32_e32 v9, 0xffff0000, v48
	v_lshlrev_b32_e32 v10, 16, v49
	v_and_b32_e32 v11, 0xffff0000, v49
	v_lshlrev_b32_e32 v12, 16, v50
	v_and_b32_e32 v13, 0xffff0000, v50
	v_lshlrev_b32_e32 v14, 16, v51
	v_and_b32_e32 v15, 0xffff0000, v51
	v_pk_add_f32 v[80:81], v[80:81], v[8:9]
	v_pk_add_f32 v[82:83], v[82:83], v[10:11]
	v_pk_add_f32 v[84:85], v[84:85], v[12:13]
	v_pk_add_f32 v[86:87], v[86:87], v[14:15]
	s_waitcnt lgkmcnt(6)
	v_lshlrev_b32_e32 v8, 16, v52
	v_and_b32_e32 v9, 0xffff0000, v52
	v_lshlrev_b32_e32 v10, 16, v53
	v_and_b32_e32 v11, 0xffff0000, v53
	v_lshlrev_b32_e32 v12, 16, v54
	v_and_b32_e32 v13, 0xffff0000, v54
	v_lshlrev_b32_e32 v14, 16, v55
	v_and_b32_e32 v15, 0xffff0000, v55
	v_pk_add_f32 v[80:81], v[80:81], v[8:9]
	v_pk_add_f32 v[82:83], v[82:83], v[10:11]
	v_pk_add_f32 v[84:85], v[84:85], v[12:13]
	v_pk_add_f32 v[86:87], v[86:87], v[14:15]
	s_waitcnt lgkmcnt(5)
	v_lshlrev_b32_e32 v8, 16, v56
	v_and_b32_e32 v9, 0xffff0000, v56
	v_lshlrev_b32_e32 v10, 16, v57
	v_and_b32_e32 v11, 0xffff0000, v57
	v_lshlrev_b32_e32 v12, 16, v58
	v_and_b32_e32 v13, 0xffff0000, v58
	v_lshlrev_b32_e32 v14, 16, v59
	v_and_b32_e32 v15, 0xffff0000, v59
	v_pk_add_f32 v[80:81], v[80:81], v[8:9]
	v_pk_add_f32 v[82:83], v[82:83], v[10:11]
	v_pk_add_f32 v[84:85], v[84:85], v[12:13]
	v_pk_add_f32 v[86:87], v[86:87], v[14:15]
	s_waitcnt lgkmcnt(4)
	v_lshlrev_b32_e32 v8, 16, v60
	v_and_b32_e32 v9, 0xffff0000, v60
	v_lshlrev_b32_e32 v10, 16, v61
	v_and_b32_e32 v11, 0xffff0000, v61
	v_lshlrev_b32_e32 v12, 16, v62
	v_and_b32_e32 v13, 0xffff0000, v62
	v_lshlrev_b32_e32 v14, 16, v63
	v_and_b32_e32 v15, 0xffff0000, v63
	v_pk_add_f32 v[80:81], v[80:81], v[8:9]
	v_pk_add_f32 v[82:83], v[82:83], v[10:11]
	v_pk_add_f32 v[84:85], v[84:85], v[12:13]
	v_pk_add_f32 v[86:87], v[86:87], v[14:15]
	s_waitcnt lgkmcnt(3)
	v_lshlrev_b32_e32 v8, 16, v64
	v_and_b32_e32 v9, 0xffff0000, v64
	v_lshlrev_b32_e32 v10, 16, v65
	v_and_b32_e32 v11, 0xffff0000, v65
	v_lshlrev_b32_e32 v12, 16, v66
	v_and_b32_e32 v13, 0xffff0000, v66
	v_lshlrev_b32_e32 v14, 16, v67
	v_and_b32_e32 v15, 0xffff0000, v67
	v_pk_add_f32 v[80:81], v[80:81], v[8:9]
	v_pk_add_f32 v[82:83], v[82:83], v[10:11]
	v_pk_add_f32 v[84:85], v[84:85], v[12:13]
	v_pk_add_f32 v[86:87], v[86:87], v[14:15]
	s_waitcnt lgkmcnt(2)
	v_lshlrev_b32_e32 v8, 16, v68
	v_and_b32_e32 v9, 0xffff0000, v68
	v_lshlrev_b32_e32 v10, 16, v69
	v_and_b32_e32 v11, 0xffff0000, v69
	v_lshlrev_b32_e32 v12, 16, v70
	v_and_b32_e32 v13, 0xffff0000, v70
	v_lshlrev_b32_e32 v14, 16, v71
	v_and_b32_e32 v15, 0xffff0000, v71
	v_pk_add_f32 v[80:81], v[80:81], v[8:9]
	v_pk_add_f32 v[82:83], v[82:83], v[10:11]
	v_pk_add_f32 v[84:85], v[84:85], v[12:13]
	v_pk_add_f32 v[86:87], v[86:87], v[14:15]
	s_waitcnt lgkmcnt(1)
	v_lshlrev_b32_e32 v8, 16, v72
	v_and_b32_e32 v9, 0xffff0000, v72
	v_lshlrev_b32_e32 v10, 16, v73
	v_and_b32_e32 v11, 0xffff0000, v73
	v_lshlrev_b32_e32 v12, 16, v74
	v_and_b32_e32 v13, 0xffff0000, v74
	v_lshlrev_b32_e32 v14, 16, v75
	v_and_b32_e32 v15, 0xffff0000, v75
	v_pk_add_f32 v[80:81], v[80:81], v[8:9]
	v_pk_add_f32 v[82:83], v[82:83], v[10:11]
	v_pk_add_f32 v[84:85], v[84:85], v[12:13]
	v_pk_add_f32 v[86:87], v[86:87], v[14:15]
	s_waitcnt lgkmcnt(0)
	v_lshlrev_b32_e32 v8, 16, v76
	v_and_b32_e32 v9, 0xffff0000, v76
	v_lshlrev_b32_e32 v10, 16, v77
	v_and_b32_e32 v11, 0xffff0000, v77
	v_lshlrev_b32_e32 v12, 16, v78
	v_and_b32_e32 v13, 0xffff0000, v78
	v_lshlrev_b32_e32 v14, 16, v79
	v_and_b32_e32 v15, 0xffff0000, v79
	v_pk_add_f32 v[80:81], v[80:81], v[8:9]
	v_pk_add_f32 v[82:83], v[82:83], v[10:11]
	v_pk_add_f32 v[84:85], v[84:85], v[12:13]
	v_pk_add_f32 v[86:87], v[86:87], v[14:15]
	v_pk_fma_f32 v[80:81], v[96:97], v[80:81], v[88:89] op_sel_hi:[0,1,1] neg_lo:[0,0,1] neg_hi:[0,0,1]
	v_pk_fma_f32 v[82:83], v[96:97], v[82:83], v[90:91] op_sel_hi:[0,1,1] neg_lo:[0,0,1] neg_hi:[0,0,1]
	v_pk_fma_f32 v[84:85], v[96:97], v[84:85], v[92:93] op_sel_hi:[0,1,1] neg_lo:[0,0,1] neg_hi:[0,0,1]
	v_pk_fma_f32 v[86:87], v[96:97], v[86:87], v[94:95] op_sel_hi:[0,1,1] neg_lo:[0,0,1] neg_hi:[0,0,1]
	v_cvt_pk_bf16_f32 v8, v80, v81
	v_cvt_pk_bf16_f32 v9, v82, v83
	v_cvt_pk_bf16_f32 v10, v84, v85
	v_cvt_pk_bf16_f32 v11, v86, v87
	v_add_u32_e32 v98, 0x1800000, v0
	global_store_dwordx4 v98, v[8:11], s[10:11]
	s_add_i32 s20, s20, 1
	s_add_i32 s14, s14, 1
	s_cmp_lt_u32 s14, 2
	s_cbranch_scc1 .Lpool_tp
	s_add_i32 s5, s5, s16
	s_waitcnt lgkmcnt(0)
	s_barrier
	s_branch .Lpool_blk
.Lpool_end:
	s_mov_b64 exec, s[6:7]
